# K1 saddr-form LDS-DMA in GEMM K-loops + post-prologue grid sync done by the kernel own XCD barrier instead of cooperative-groups sync
# speedup vs baseline: 1.0171x; 1.0034x over previous
; #define LAS __attribute__((address_space(3)))
; __device__ __forceinline__ unsigned xb_xcc_id() { return (unsigned)__builtin_amdgcn_s_getreg((3 << 11) | 20) & 0xFu; }
; #define P_WS() (rd_ptr(24))
; __global__ void __launch_bounds__(NTHR, 2) trunk_fwd(Args args) {
;     ...
;         if (!SKP) prologue(args, args.ws, lds, (int)blockIdx.x * NWAVES + wave, (int)gridDim.x * NWAVES, wave, lane);
;     }
;     grid.sync();
;     constexpr int NREP = (REPMASK || REPSYNC) ? 2 : 1;
;     for (int it_ = 0; it_ < 32 * NREP; ++it_) {
;     ...
;         { XcdBarrier bar; bar.bar = (unsigned*)(P_WS() + WS_BAR); bar.x = xb_xcc_id(); bar.st = (volatile LAS unsigned*)(lds + MISC_OFF); xcd_barrier(bar); }
.LBB0_861:
	s_mul_i32 s0, s55, s54
	s_mul_i32 s83, s0, s24
	s_add_i32 s0, 0, 0x19000
	v_writelane_b32 v255, s0, 6
	s_add_i32 s0, 0, 0x22004
	v_writelane_b32 v255, s0, 7
	v_mov_b32_e32 v231, 0x210c0
	s_movk_i32 s80, 0x2000
	s_mov_b32 s81, 0x10000
	v_mov_b32_e32 v221, 0
	s_movk_i32 s96, 0x4000
	s_movk_i32 s90, 0x80
	s_movk_i32 s29, 0x1600
	s_movk_i32 s84, 0x33c0
	s_movk_i32 s85, 0x1000
	s_mov_b32 s25, 0x800000
	v_mov_b32_e32 v234, 0xff800000
	s_movk_i32 s24, 0x7fff
	v_mov_b32_e32 v235, 0x358637bd
	s_movk_i32 s86, 0x3fc0
	v_mov_b32_e32 v237, 1
	v_mov_b32_e32 v238, 0x41b17218
	v_bfrev_b32_e32 v244, 0.5
	v_mov_b32_e32 v245, 0x160000
	s_mov_b32 s87, 0x42000
	s_mov_b32 s43, 0x41000000
	s_movk_i32 s88, 0x37c0
	s_movk_i32 s89, 0x3bc0
	s_mov_b32 s52, -1
	s_mov_b32 s31, 0
	s_mov_b64 s[34:35], 0x4000
	s_mov_b32 s36, 0x3b808081
	s_mov_b32 s38, 0xbfb8aa3b
	s_mov_b64 s[44:45], 0x18408000
	s_mov_b64 s[46:47], 0x19404000
	s_mov_b64 s[48:49], 0x19484000
	v_writelane_b32 v255, s83, 8
	s_branch .LBB0_1363
